# on top of v20: attention per-pattern output stores widened from sixteen 8-byte to eight... four 16-byte stores per accumulator pair using v_permlane32_swap (same bytes, same addresses)
# speedup vs baseline: 1.0102x; 1.0102x over previous
; #define LAS __attribute__((address_space(3)))
; __device__ __forceinline__ void attn_mfma(const GAS bf16* proj, GAS bf16* part, GAS float* lse, int TOKG, const GAS float* qgain, const GAS float* kgain, const GAS float* rel_bias,
;                                           unsigned char* lds, int tid, int lane, int wave, int bid, int G) {
;     ...
;     for (int u = bid; u < nunits; u += G) {
;         ATT_DEC(u, )
;         __syncthreads();
;         if (tid < 192) { float tv = -INFINITY; const int dl = 160 - tid;
;             if (dl >= 0 && dl <= 128) tv = rel_bias[bkt[p * 129 + dl] * 16 + h] * 1.4426950408889634f;
;             ((LAS float*)(L + ATT_BIAS))[tid] = tv; }
; #pragma unroll
;         for (int j = 0; j < 3; ++j) {
;             const int kk0 = 2 * rp2 + 128 * j;
; #pragma unroll
;             for (int e2 = 0; e2 < 2; ++e2) { const int it = 2 * j + e2, kk = kk0 + e2;
;                 *(LAS v4u*)(L + ATT_KS + kk * ATT_KSTR + c8 * 16) = kwr[it];
;                 *(LAS v4u*)(L + ATT_VT + kk * ATT_VSTR + c8 * 16) = vwr[it]; }
;         }
;         const size_t orow = rowb + ((size_t)(m0 + 32 * wave + c) << dsh) + r;
;         bf16x8 qf[4];
; #pragma unroll
;         for (int s = 0; s < 4; ++s) qf[s] = __builtin_bit_cast(bf16x8, qwr[s]);
;         if (u + G < nunits) ATT_ISSUE(u + G);
.LBB0_289:
	s_or_b64 exec, exec, s[10:11]
	s_waitcnt vmcnt(4)
	v_mov_b64_e32 v[80:81], v[174:175]
	v_mov_b64_e32 v[84:85], v[166:167]
	v_mov_b64_e32 v[88:89], v[162:163]
	v_mov_b64_e32 v[92:93], v[170:171]
	s_and_b64 vcc, exec, s[28:29]
	v_mov_b64_e32 v[82:83], v[176:177]
	v_mov_b64_e32 v[86:87], v[168:169]
	v_mov_b64_e32 v[90:91], v[164:165]
	v_mov_b64_e32 v[94:95], v[172:173]
	s_mov_b32 s14, s37
	s_cbranch_vccnz .LBB0_328

; #define GAS __attribute__((address_space(1)))
; __device__ __forceinline__ unsigned pkbf(float lo, float hi) { const f32x2_t v = {lo, hi}; const bf16x2_t b = __builtin_convertvector(v, bf16x2_t); return __builtin_bit_cast(unsigned, b); }
; __device__ __forceinline__ void attn_mfma(const GAS bf16* proj, GAS bf16* part, GAS float* lse, int TOKG, const GAS float* qgain, const GAS float* kgain, const GAS float* rel_bias,
;                                           unsigned char* lds, int tid, int lane, int wave, int bid, int G) {
;     ...
;         const float inv = __builtin_amdgcn_rcpf(l);
;         GAS bf16* op = part + ((size_t)p * TOKG + orow) * 1024 + h * 64 + 4 * hh;
; #pragma unroll
;         for (int dt = 0; dt < 2; ++dt)
; #pragma unroll
;             for (int g4 = 0; g4 < 4; ++g4) { v2u w; w.x = pkbf(o[dt][4 * g4] * inv, o[dt][4 * g4 + 1] * inv); w.y = pkbf(o[dt][4 * g4 + 2] * inv, o[dt][4 * g4 + 3] * inv);
;                 *(GAS v2u*)(op + 32 * dt + 8 * g4) = w; }
;         if (hh == 0) lse[((size_t)p * TOKG + orow) * 16 + h] = __logf(l);
.LBB0_324:
	s_lshl_b32 s10, -1, s40
	s_andn2_b32 s12, s42, s10
	s_ashr_i32 s10, s39, 4
	s_ashr_i32 s11, s10, 31
	s_lshl_b64 s[10:11], s[10:11], 13
	s_mul_hi_i32 s13, s38, s34
	s_mul_i32 s38, s38, s34
	s_add_u32 s10, s10, s38
	v_lshl_add_u32 v212, s43, 8, v195
	s_addc_u32 s11, s11, s13
	v_ashrrev_i32_e32 v213, 31, v212
	s_waitcnt lgkmcnt(0)
	v_add_f32_e32 v183, v183, v184
	s_add_u32 s10, s10, s12
	v_lshlrev_b64 v[212:213], s40, v[212:213]
	v_rcp_f32_e32 v214, v183
	s_addc_u32 s11, s11, 0
	v_lshl_add_u64 v[184:185], s[10:11], 0, v[212:213]
	v_lshlrev_b64 v[212:213], 11, v[184:185]
	v_lshl_add_u64 v[212:213], s[24:25], 0, v[212:213]
	s_lshl_b32 s60, s36, 7
	v_lshl_add_u64 v[212:213], v[212:213], 0, s[60:61]
	v_pk_mul_f32 v[96:97], v[214:215], v[96:97] op_sel_hi:[0,1]
	v_pk_mul_f32 v[98:99], v[214:215], v[98:99] op_sel_hi:[0,1]
	v_pk_mul_f32 v[100:101], v[214:215], v[100:101] op_sel_hi:[0,1]
	v_pk_mul_f32 v[102:103], v[214:215], v[102:103] op_sel_hi:[0,1]
	v_pk_mul_f32 v[104:105], v[214:215], v[104:105] op_sel_hi:[0,1]
	v_pk_mul_f32 v[106:107], v[214:215], v[106:107] op_sel_hi:[0,1]
	v_pk_mul_f32 v[108:109], v[214:215], v[108:109] op_sel_hi:[0,1]
	v_pk_mul_f32 v[110:111], v[214:215], v[110:111] op_sel_hi:[0,1]
	v_pk_mul_f32 v[80:81], v[214:215], v[80:81] op_sel_hi:[0,1]
	v_pk_mul_f32 v[82:83], v[214:215], v[82:83] op_sel_hi:[0,1]
	v_pk_mul_f32 v[84:85], v[214:215], v[84:85] op_sel_hi:[0,1]
	v_pk_mul_f32 v[86:87], v[214:215], v[86:87] op_sel_hi:[0,1]
	v_pk_mul_f32 v[88:89], v[214:215], v[88:89] op_sel_hi:[0,1]
	v_pk_mul_f32 v[90:91], v[214:215], v[90:91] op_sel_hi:[0,1]
	v_pk_mul_f32 v[92:93], v[214:215], v[92:93] op_sel_hi:[0,1]
	v_pk_mul_f32 v[94:95], v[214:215], v[94:95] op_sel_hi:[0,1]
	v_lshl_add_u64 v[212:213], v[212:213], 0, v[112:113]
	v_lshl_add_u64 v[212:213], v[212:213], 0, v[112:113]
	v_cvt_pk_bf16_f32 v220, v96, v97
	v_cvt_pk_bf16_f32 v221, v98, v99
	v_cvt_pk_bf16_f32 v222, v100, v101
	v_cvt_pk_bf16_f32 v223, v102, v103
	v_cvt_pk_bf16_f32 v224, v104, v105
	v_cvt_pk_bf16_f32 v225, v106, v107
	v_cvt_pk_bf16_f32 v226, v108, v109
	v_cvt_pk_bf16_f32 v227, v110, v111
	v_cvt_pk_bf16_f32 v228, v80, v81
	v_cvt_pk_bf16_f32 v229, v82, v83
	v_cvt_pk_bf16_f32 v230, v84, v85
	v_cvt_pk_bf16_f32 v231, v86, v87
	v_cvt_pk_bf16_f32 v232, v88, v89
	v_cvt_pk_bf16_f32 v233, v90, v91
	v_cvt_pk_bf16_f32 v234, v92, v93
	v_cvt_pk_bf16_f32 v235, v94, v95
	s_nop 1
	v_permlane32_swap_b32_e32 v220, v222
	v_permlane32_swap_b32_e32 v221, v223
	v_permlane32_swap_b32_e32 v224, v226
	v_permlane32_swap_b32_e32 v225, v227
	v_permlane32_swap_b32_e32 v228, v230
	v_permlane32_swap_b32_e32 v229, v231
	v_permlane32_swap_b32_e32 v232, v234
	v_permlane32_swap_b32_e32 v233, v235
	global_store_dwordx4 v[212:213], v[220:223], off
	global_store_dwordx4 v[212:213], v[224:227], off offset:32
	global_store_dwordx4 v[212:213], v[228:231], off offset:64
	global_store_dwordx4 v[212:213], v[232:235], off offset:96
	s_and_saveexec_b64 s[10:11], s[8:9]
	s_cbranch_execz .LBB0_289
	v_cmp_gt_f32_e32 vcc, s92, v183
	s_lshl_b32 s60, s36, 2
	s_nop 0
	v_cndmask_b32_e64 v80, 0, 32, vcc
	v_ldexp_f32 v80, v183, v80
	v_log_f32_e32 v80, v80
	v_cndmask_b32_e32 v81, 0, v191, vcc
	v_mul_f32_e32 v82, 0x3f317217, v80
	v_fma_f32 v82, v80, s64, -v82
	v_fmac_f32_e32 v82, 0x3377d1cf, v80
	v_fmac_f32_e32 v82, 0x3f317217, v80
	v_cmp_lt_f32_e64 vcc, |v80|, s65
	s_nop 1
	v_cndmask_b32_e32 v80, v80, v82, vcc
	v_sub_f32_e32 v82, v80, v81
	v_lshlrev_b64 v[80:81], 6, v[184:185]
	v_lshl_add_u64 v[80:81], s[0:1], 0, v[80:81]
	v_lshl_add_u64 v[80:81], v[80:81], 0, s[60:61]
	global_store_dword v[80:81], v82, off
	s_branch .LBB0_289
